# S5 scan second pass: v_cvt_pk_bf16_f32 replaces the 3-op bf16 rounding bit trick (64 sites, 2 stores each)
# speedup vs baseline: 1.0010x; 1.0010x over previous
; __device__ __forceinline__ unsigned xb_ld(unsigned* p)              { return __hip_atomic_load(p, __ATOMIC_RELAXED, __HIP_MEMORY_SCOPE_AGENT); }
; __device__ __forceinline__ unsigned xb_add(unsigned* p, unsigned v) { return __hip_atomic_fetch_add(p, v, __ATOMIC_RELAXED, __HIP_MEMORY_SCOPE_AGENT); }
; #define XB_SPIN(cond, bar) do { unsigned _sp = 0; while (cond) { __builtin_amdgcn_s_sleep(1); \
;     if ((++_sp & 255u) == 0u) { if (xb_ld(&(bar)[XB_TMO])) break; if (_sp > XB_SPIN_CAP) { atomicAdd(&(bar)[XB_TMO], 1u); break; } } } } while (0)
; __device__ __forceinline__ void xcd_barrier(const XcdBarrier& b) {
;     asm volatile("s_waitcnt vmcnt(0)" ::: "memory");
;     __syncthreads();
;     if (threadIdx.x == 0) {
;         unsigned* bar = b.bar;
;         __builtin_amdgcn_s_waitcnt(0);
;         unsigned nloc = b.st[0], nx = b.st[1];
;         if (nloc == 0u) { xcd_barrier_complete(bar, b.x, nloc, nx); b.st[0] = nloc; b.st[1] = nx; }
;         const unsigned old = xb_add(&bar[XB_XSUB(b.x)], 1u);
;         const unsigned gen = old / nloc;
;         if (old + 1u == (gen + 1u) * nloc) {
;             __builtin_amdgcn_fence(__ATOMIC_RELEASE, "agent");
;             asm volatile("s_waitcnt vmcnt(0)" ::: "memory");
;             const unsigned og = xb_add(&bar[XB_TOP], 1u);
;             const unsigned tg = og / nx;
;             if (og + 1u == (tg + 1u) * nx) xb_add(&bar[XB_TOPGEN], 1u);
;             else XB_SPIN(xb_ld(&bar[XB_TOPGEN]) == tg, bar);
;             __builtin_amdgcn_fence(__ATOMIC_ACQUIRE, "agent");
;             xb_add(&bar[XB_XGEN(b.x)], 1u);
;             asm volatile("s_waitcnt vmcnt(0)" ::: "memory");
;         } else {
;             XB_SPIN(xb_ld(&bar[XB_XGEN(b.x)]) == gen, bar);
;             __builtin_amdgcn_fence(__ATOMIC_ACQUIRE, "agent");
;             asm volatile("s_waitcnt vmcnt(0)" ::: "memory");
;         }
;     }
;     __syncthreads();
; }
.LBB0_252:
	s_cmp_gt_i32 s85, 2
	s_cselect_b64 s[2:3], -1, 0
	s_and_b64 s[4:5], s[6:7], s[2:3]
	s_andn2_b64 vcc, exec, s[4:5]
	s_cbranch_vccnz .LBB0_306
	s_waitcnt vmcnt(0)
	s_barrier
	s_mov_b64 s[4:5], exec
	v_readlane_b32 s6, v251, 18
	v_readlane_b32 s7, v251, 19
	s_and_b64 s[6:7], s[4:5], s[6:7]
	s_mov_b64 exec, s[6:7]
	s_cbranch_execz .LBB0_305
	buffer_inv sc1
	s_and_b32 s10, s88, 7
	s_lshl_b32 s10, s10, 3
	s_bfe_u32 s11, s88, 0x30003
	s_or_b32 s10, s10, s11
	s_lshl_b32 s10, s10, 8
	s_add_u32 s12, s66, 0xfd09000
	s_addc_u32 s13, s67, 0
	v_mov_b32_e32 v1, s10
	v_mov_b32_e32 v2, 1
	global_atomic_add v1, v2, s[12:13]
	s_movk_i32 s11, 4
	s_mov_b32 s14, 0
	v_mov_b32_e32 v5, 0x6000

; __device__ __forceinline__ unsigned f2bf(float f) { unsigned u = __builtin_bit_cast(unsigned, f); return (u + 0x7fffu + ((u >> 16) & 1u)) >> 16; }
; __global__ void __launch_bounds__(NWAVES * 64, 2) mega_fwd(Args args) {
;     ...
;             for (int q = 0; q < 64; ++q) { const int sidx = seg * 64 + q, c = dir ? 511 - sidx : sidx; const float nr = ar * sr - ai * si + er[q], ni = ar * si + ai * sr + ei[q]; sr = nr; si = ni;
;                 const int cd = dir ? c - 1 : c + 1;
;                 if (cd >= 0 && cd < 512) { Ab[(size_t)cd * 512] = (bf16)f2bf(sr); Ab[(size_t)cd * 512 + 64] = (bf16)f2bf(si); } }
.LBB0_690:
	s_and_b64 s[40:41], s[40:41], exec
	v_pk_mul_f32 v[90:91], v[86:87], v[92:93]
	s_cselect_b32 s1, 1, -1
	v_sub_f32_e32 v3, v90, v91
	v_mul_f32_e32 v90, v86, v93
	v_fmac_f32_e32 v90, v87, v92
	s_add_i32 s3, s64, s1
	v_add_f32_e32 v3, v3, v147
	s_cmpk_gt_u32 s3, 0x1ff
	v_add_f32_e32 v90, v90, v145
	s_cbranch_scc1 .LBB0_692
	s_lshl_b32 s10, s3, 10
	v_cvt_pk_bf16_f32 v91, v3, v90
	v_lshl_add_u64 v[92:93], v[88:89], 0, s[10:11]
	global_store_short v[92:93], v91, off offset:512
	global_store_short_d16_hi v[92:93], v91, off offset:640
.LBB0_692:
	v_mul_f32_e32 v91, v87, v90
	v_fma_f32 v91, v86, v3, -v91
	v_mul_f32_e32 v3, v87, v3
	v_fmac_f32_e32 v3, v86, v90
	s_add_i32 s3, s62, s1
	v_add_f32_e32 v82, v91, v82
	s_cmpk_gt_u32 s3, 0x1ff
	v_add_f32_e32 v83, v3, v83
	s_cbranch_scc1 .LBB0_694
	s_lshl_b32 s10, s3, 10
	v_cvt_pk_bf16_f32 v3, v82, v83
	v_lshl_add_u64 v[90:91], v[88:89], 0, s[10:11]
	global_store_short v[90:91], v3, off offset:512
	global_store_short_d16_hi v[90:91], v3, off offset:640
.LBB0_694:
	v_mul_f32_e32 v3, v87, v83
	v_fma_f32 v3, v86, v82, -v3
	v_mul_f32_e32 v82, v87, v82
	v_fmac_f32_e32 v82, v86, v83
	s_add_i32 s3, s38, s1
	v_add_f32_e32 v3, v3, v143
	s_cmpk_gt_u32 s3, 0x1ff
	v_add_f32_e32 v82, v82, v141
	s_cbranch_scc1 .LBB0_696
	s_lshl_b32 s10, s3, 10
	v_cvt_pk_bf16_f32 v83, v3, v82
	v_lshl_add_u64 v[90:91], v[88:89], 0, s[10:11]
	global_store_short v[90:91], v83, off offset:512
	global_store_short_d16_hi v[90:91], v83, off offset:640
.LBB0_696:
	v_mul_f32_e32 v83, v87, v82
	v_fma_f32 v83, v86, v3, -v83
	v_mul_f32_e32 v3, v87, v3
	v_fmac_f32_e32 v3, v86, v82
	s_add_i32 s3, s4, s1
	v_add_f32_e32 v78, v83, v78
	s_cmpk_gt_u32 s3, 0x1ff
	v_add_f32_e32 v79, v3, v79
	s_cbranch_scc1 .LBB0_698
	s_lshl_b32 s10, s3, 10
	v_cvt_pk_bf16_f32 v3, v78, v79
	v_lshl_add_u64 v[82:83], v[88:89], 0, s[10:11]
	global_store_short v[82:83], v3, off offset:512
	global_store_short_d16_hi v[82:83], v3, off offset:640
.LBB0_698:
	v_mul_f32_e32 v3, v87, v79
	v_fma_f32 v3, v86, v78, -v3
	v_mul_f32_e32 v78, v87, v78
	v_fmac_f32_e32 v78, v86, v79
	s_add_i32 s3, s36, s1
	v_add_f32_e32 v3, v3, v139
	s_cmpk_gt_u32 s3, 0x1ff
	v_add_f32_e32 v78, v78, v137
	s_cbranch_scc1 .LBB0_700
	s_lshl_b32 s10, s3, 10
	v_cvt_pk_bf16_f32 v79, v3, v78
	v_lshl_add_u64 v[82:83], v[88:89], 0, s[10:11]
	global_store_short v[82:83], v79, off offset:512
	global_store_short_d16_hi v[82:83], v79, off offset:640
.LBB0_700:
	v_mul_f32_e32 v79, v87, v78
	v_fma_f32 v79, v86, v3, -v79
	v_mul_f32_e32 v3, v87, v3
	v_fmac_f32_e32 v3, v86, v78
	s_add_i32 s3, s96, s1
	v_add_f32_e32 v74, v79, v74
	s_cmpk_gt_u32 s3, 0x1ff
	v_add_f32_e32 v75, v3, v75
	s_cbranch_scc1 .LBB0_702
	s_lshl_b32 s10, s3, 10
	v_cvt_pk_bf16_f32 v3, v74, v75
	v_lshl_add_u64 v[78:79], v[88:89], 0, s[10:11]
	global_store_short v[78:79], v3, off offset:512
	global_store_short_d16_hi v[78:79], v3, off offset:640
.LBB0_702:
	v_mul_f32_e32 v3, v87, v75
	v_fma_f32 v3, v86, v74, -v3
	v_mul_f32_e32 v74, v87, v74
	v_fmac_f32_e32 v74, v86, v75
	s_add_i32 s3, s92, s1
	v_add_f32_e32 v3, v3, v135
	s_cmpk_gt_u32 s3, 0x1ff
	v_add_f32_e32 v74, v74, v133
	s_cbranch_scc1 .LBB0_704
	s_lshl_b32 s10, s3, 10
	v_cvt_pk_bf16_f32 v75, v3, v74
	v_lshl_add_u64 v[78:79], v[88:89], 0, s[10:11]
	global_store_short v[78:79], v75, off offset:512
	global_store_short_d16_hi v[78:79], v75, off offset:640
.LBB0_704:
	v_mul_f32_e32 v75, v87, v74
	v_fma_f32 v75, v86, v3, -v75
	v_mul_f32_e32 v3, v87, v3
	v_fmac_f32_e32 v3, v86, v74
	s_add_i32 s3, s86, s1
	v_add_f32_e32 v70, v75, v70
	s_cmpk_gt_u32 s3, 0x1ff
	v_add_f32_e32 v3, v3, v71
	s_cbranch_scc1 .LBB0_706
	s_lshl_b32 s10, s3, 10
	v_cvt_pk_bf16_f32 v71, v70, v3
	v_lshl_add_u64 v[74:75], v[88:89], 0, s[10:11]
	global_store_short v[74:75], v71, off offset:512
	global_store_short_d16_hi v[74:75], v71, off offset:640
.LBB0_706:
	v_mul_f32_e32 v71, v87, v3
	v_fma_f32 v71, v86, v70, -v71
	v_mul_f32_e32 v70, v87, v70
	v_fmac_f32_e32 v70, v86, v3
	s_add_i32 s3, s78, s1
	v_add_f32_e32 v71, v71, v131
	s_cmpk_gt_u32 s3, 0x1ff
	v_add_f32_e32 v70, v70, v129
	s_cbranch_scc1 .LBB0_708
	s_lshl_b32 s10, s3, 10
	v_cvt_pk_bf16_f32 v3, v71, v70
	v_lshl_add_u64 v[74:75], v[88:89], 0, s[10:11]
	global_store_short v[74:75], v3, off offset:512
	global_store_short_d16_hi v[74:75], v3, off offset:640
.LBB0_708:
	v_mul_f32_e32 v3, v87, v70
	v_fma_f32 v3, v86, v71, -v3
	v_add_f32_e32 v3, v3, v66
	v_mul_f32_e32 v66, v87, v71
	v_fmac_f32_e32 v66, v86, v70
	s_add_i32 s3, s50, s1
	v_readlane_b32 s78, v251, 62
	s_cmpk_gt_u32 s3, 0x1ff
	v_add_f32_e32 v67, v66, v67
	v_readlane_b32 s79, v251, 63
	s_cbranch_scc1 .LBB0_710
	s_lshl_b32 s10, s3, 10
	v_cvt_pk_bf16_f32 v66, v3, v67
	v_lshl_add_u64 v[70:71], v[88:89], 0, s[10:11]
	global_store_short v[70:71], v66, off offset:512
	global_store_short_d16_hi v[70:71], v66, off offset:640
.LBB0_710:
	v_mul_f32_e32 v66, v87, v67
	v_fma_f32 v66, v86, v3, -v66
	v_mul_f32_e32 v3, v87, v3
	v_fmac_f32_e32 v3, v86, v67
	s_add_i32 s3, s84, s1
	v_add_f32_e32 v66, v66, v127
	s_cmpk_gt_u32 s3, 0x1ff
	v_add_f32_e32 v67, v3, v125
	s_cbranch_scc1 .LBB0_712
	s_lshl_b32 s10, s3, 10
	v_cvt_pk_bf16_f32 v3, v66, v67
	v_lshl_add_u64 v[70:71], v[88:89], 0, s[10:11]
	global_store_short v[70:71], v3, off offset:512
	global_store_short_d16_hi v[70:71], v3, off offset:640
.LBB0_712:
	v_mul_f32_e32 v3, v87, v67
	v_fma_f32 v3, v86, v66, -v3
	v_add_f32_e32 v3, v3, v62
	v_mul_f32_e32 v62, v87, v66
	v_fmac_f32_e32 v62, v86, v67
	s_add_i32 s3, s26, s1
	s_cmpk_gt_u32 s3, 0x1ff
	v_add_f32_e32 v63, v62, v63
	s_cbranch_scc1 .LBB0_714
	s_lshl_b32 s10, s3, 10
	v_cvt_pk_bf16_f32 v62, v3, v63
	v_lshl_add_u64 v[66:67], v[88:89], 0, s[10:11]
	global_store_short v[66:67], v62, off offset:512
	global_store_short_d16_hi v[66:67], v62, off offset:640
; __device__ __forceinline__ unsigned f2bf(float f) { unsigned u = __builtin_bit_cast(unsigned, f); return (u + 0x7fffu + ((u >> 16) & 1u)) >> 16; }
; __global__ void __launch_bounds__(NWAVES * 64, 2) mega_fwd(Args args) {
;     ...
;             for (int q = 0; q < 64; ++q) { const int sidx = seg * 64 + q, c = dir ? 511 - sidx : sidx; const float nr = ar * sr - ai * si + er[q], ni = ar * si + ai * sr + ei[q]; sr = nr; si = ni;
;                 const int cd = dir ? c - 1 : c + 1;
;                 if (cd >= 0 && cd < 512) { Ab[(size_t)cd * 512] = (bf16)f2bf(sr); Ab[(size_t)cd * 512 + 64] = (bf16)f2bf(si); } }
.LBB0_714:
	v_mul_f32_e32 v62, v87, v63
	v_fma_f32 v62, v86, v3, -v62
	v_mul_f32_e32 v3, v87, v3
	v_fmac_f32_e32 v3, v86, v63
	s_add_i32 s3, s22, s1
	v_add_f32_e32 v62, v62, v123
	s_cmpk_gt_u32 s3, 0x1ff
	v_add_f32_e32 v63, v3, v121
	s_cbranch_scc1 .LBB0_716
	s_lshl_b32 s10, s3, 10
	v_cvt_pk_bf16_f32 v3, v62, v63
	v_lshl_add_u64 v[66:67], v[88:89], 0, s[10:11]
	global_store_short v[66:67], v3, off offset:512
	global_store_short_d16_hi v[66:67], v3, off offset:640
.LBB0_716:
	v_mul_f32_e32 v3, v87, v63
	v_fma_f32 v3, v86, v62, -v3
	v_mul_f32_e32 v62, v87, v62
	v_fmac_f32_e32 v62, v86, v63
	s_add_i32 s3, s8, s1
	v_add_f32_e32 v3, v3, v84
	s_cmpk_gt_u32 s3, 0x1ff
	v_add_f32_e32 v63, v62, v85
	s_cbranch_scc1 .LBB0_718
	s_lshl_b32 s10, s3, 10
	v_cvt_pk_bf16_f32 v62, v3, v63
	v_lshl_add_u64 v[66:67], v[88:89], 0, s[10:11]
	global_store_short v[66:67], v62, off offset:512
	global_store_short_d16_hi v[66:67], v62, off offset:640
.LBB0_718:
	v_mul_f32_e32 v62, v87, v63
	v_fma_f32 v62, v86, v3, -v62
	v_mul_f32_e32 v3, v87, v3
	v_fmac_f32_e32 v3, v86, v63
	s_add_i32 s3, s6, s1
	v_add_f32_e32 v62, v62, v146
	s_cmpk_gt_u32 s3, 0x1ff
	v_add_f32_e32 v63, v3, v144
	s_cbranch_scc1 .LBB0_720
	s_lshl_b32 s10, s3, 10
	v_cvt_pk_bf16_f32 v3, v62, v63
	v_lshl_add_u64 v[66:67], v[88:89], 0, s[10:11]
	global_store_short v[66:67], v3, off offset:512
	global_store_short_d16_hi v[66:67], v3, off offset:640
.LBB0_720:
	v_mul_f32_e32 v3, v87, v63
	v_fma_f32 v3, v86, v62, -v3
	v_mul_f32_e32 v62, v87, v62
	v_fmac_f32_e32 v62, v86, v63
	s_add_i32 s3, s80, s1
	v_add_f32_e32 v3, v3, v80
	s_cmpk_gt_u32 s3, 0x1ff
	v_add_f32_e32 v63, v62, v81
	s_cbranch_scc1 .LBB0_722
	s_lshl_b32 s10, s3, 10
	v_cvt_pk_bf16_f32 v62, v3, v63
	v_lshl_add_u64 v[66:67], v[88:89], 0, s[10:11]
	global_store_short v[66:67], v62, off offset:512
	global_store_short_d16_hi v[66:67], v62, off offset:640
.LBB0_722:
	v_mul_f32_e32 v62, v87, v63
	v_fma_f32 v62, v86, v3, -v62
	v_mul_f32_e32 v3, v87, v3
	v_fmac_f32_e32 v3, v86, v63
	s_add_i32 s3, s94, s1
	v_add_f32_e32 v62, v62, v142
	s_cmpk_gt_u32 s3, 0x1ff
	v_add_f32_e32 v63, v3, v140
	s_cbranch_scc1 .LBB0_724
	s_lshl_b32 s10, s3, 10
	v_cvt_pk_bf16_f32 v3, v62, v63
	v_lshl_add_u64 v[66:67], v[88:89], 0, s[10:11]
	global_store_short v[66:67], v3, off offset:512
	global_store_short_d16_hi v[66:67], v3, off offset:640
.LBB0_724:
	v_mul_f32_e32 v3, v87, v63
	v_fma_f32 v3, v86, v62, -v3
	v_mul_f32_e32 v62, v87, v62
	v_fmac_f32_e32 v62, v86, v63
	s_add_i32 s3, s90, s1
	v_add_f32_e32 v3, v3, v76
	s_cmpk_gt_u32 s3, 0x1ff
	v_add_f32_e32 v63, v62, v77
	s_cbranch_scc1 .LBB0_726
	s_lshl_b32 s10, s3, 10
	v_cvt_pk_bf16_f32 v62, v3, v63
	v_lshl_add_u64 v[66:67], v[88:89], 0, s[10:11]
	global_store_short v[66:67], v62, off offset:512
	global_store_short_d16_hi v[66:67], v62, off offset:640
.LBB0_726:
	v_mul_f32_e32 v62, v87, v63
	v_fma_f32 v62, v86, v3, -v62
	v_mul_f32_e32 v3, v87, v3
	v_fmac_f32_e32 v3, v86, v63
	s_add_i32 s3, s82, s1
	v_add_f32_e32 v62, v62, v138
	s_cmpk_gt_u32 s3, 0x1ff
	v_add_f32_e32 v63, v3, v136
	s_cbranch_scc1 .LBB0_728
	s_lshl_b32 s10, s3, 10
	v_cvt_pk_bf16_f32 v3, v62, v63
	v_lshl_add_u64 v[66:67], v[88:89], 0, s[10:11]
	global_store_short v[66:67], v3, off offset:512
	global_store_short_d16_hi v[66:67], v3, off offset:640
.LBB0_728:
	v_mul_f32_e32 v3, v87, v63
	v_fma_f32 v3, v86, v62, -v3
	v_mul_f32_e32 v62, v87, v62
	v_fmac_f32_e32 v62, v86, v63
	s_add_i32 s3, s74, s1
	v_add_f32_e32 v3, v3, v72
	s_cmpk_gt_u32 s3, 0x1ff
	v_add_f32_e32 v63, v62, v73
	s_cbranch_scc1 .LBB0_730
	s_lshl_b32 s10, s3, 10
	v_cvt_pk_bf16_f32 v62, v3, v63
	v_lshl_add_u64 v[66:67], v[88:89], 0, s[10:11]
	global_store_short v[66:67], v62, off offset:512
	global_store_short_d16_hi v[66:67], v62, off offset:640
.LBB0_730:
	v_mul_f32_e32 v62, v87, v63
	v_fma_f32 v62, v86, v3, -v62
	v_mul_f32_e32 v3, v87, v3
	v_fmac_f32_e32 v3, v86, v63
	s_add_i32 s3, s48, s1
	v_add_f32_e32 v62, v62, v134
	s_cmpk_gt_u32 s3, 0x1ff
	v_add_f32_e32 v63, v3, v132
	s_cbranch_scc1 .LBB0_732
	s_lshl_b32 s10, s3, 10
	v_cvt_pk_bf16_f32 v3, v62, v63
	v_lshl_add_u64 v[66:67], v[88:89], 0, s[10:11]
	global_store_short v[66:67], v3, off offset:512
	global_store_short_d16_hi v[66:67], v3, off offset:640
.LBB0_732:
	v_mul_f32_e32 v3, v87, v63
	v_fma_f32 v3, v86, v62, -v3
	v_mul_f32_e32 v62, v87, v62
	v_fmac_f32_e32 v62, v86, v63
	s_add_i32 s3, s72, s1
	v_add_f32_e32 v3, v3, v68
	s_cmpk_gt_u32 s3, 0x1ff
	v_add_f32_e32 v63, v62, v69
	s_cbranch_scc1 .LBB0_734
	s_lshl_b32 s10, s3, 10
	v_cvt_pk_bf16_f32 v62, v3, v63
	v_lshl_add_u64 v[66:67], v[88:89], 0, s[10:11]
	global_store_short v[66:67], v62, off offset:512
	global_store_short_d16_hi v[66:67], v62, off offset:640
.LBB0_734:
	v_mul_f32_e32 v62, v87, v63
	v_fma_f32 v62, v86, v3, -v62
	v_mul_f32_e32 v3, v87, v3
	v_fmac_f32_e32 v3, v86, v63
	s_add_i32 s3, s24, s1
	v_add_f32_e32 v62, v62, v130
	s_cmpk_gt_u32 s3, 0x1ff
	v_add_f32_e32 v63, v3, v128
	s_cbranch_scc1 .LBB0_736
	s_lshl_b32 s10, s3, 10
	v_cvt_pk_bf16_f32 v3, v62, v63
	v_lshl_add_u64 v[66:67], v[88:89], 0, s[10:11]
	global_store_short v[66:67], v3, off offset:512
	global_store_short_d16_hi v[66:67], v3, off offset:640
.LBB0_736:
	v_mul_f32_e32 v3, v87, v63
	v_fma_f32 v3, v86, v62, -v3
	v_mul_f32_e32 v62, v87, v62
	v_fmac_f32_e32 v62, v86, v63
	s_add_i32 s3, s20, s1
	v_add_f32_e32 v3, v3, v64
	s_cmpk_gt_u32 s3, 0x1ff
	v_add_f32_e32 v63, v62, v65
	s_cbranch_scc1 .LBB0_738
	s_lshl_b32 s10, s3, 10
	v_cvt_pk_bf16_f32 v62, v3, v63
	v_lshl_add_u64 v[64:65], v[88:89], 0, s[10:11]
	global_store_short v[64:65], v62, off offset:512
	global_store_short_d16_hi v[64:65], v62, off offset:640
; __device__ __forceinline__ unsigned f2bf(float f) { unsigned u = __builtin_bit_cast(unsigned, f); return (u + 0x7fffu + ((u >> 16) & 1u)) >> 16; }
; __global__ void __launch_bounds__(NWAVES * 64, 2) mega_fwd(Args args) {
;     ...
;             for (int q = 0; q < 64; ++q) { const int sidx = seg * 64 + q, c = dir ? 511 - sidx : sidx; const float nr = ar * sr - ai * si + er[q], ni = ar * si + ai * sr + ei[q]; sr = nr; si = ni;
;                 const int cd = dir ? c - 1 : c + 1;
;                 if (cd >= 0 && cd < 512) { Ab[(size_t)cd * 512] = (bf16)f2bf(sr); Ab[(size_t)cd * 512 + 64] = (bf16)f2bf(si); } }
.LBB0_738:
	v_mul_f32_e32 v62, v87, v63
	v_fma_f32 v62, v86, v3, -v62
	v_mul_f32_e32 v3, v87, v3
	v_fmac_f32_e32 v3, v86, v63
	s_add_i32 s3, s18, s1
	v_add_f32_e32 v62, v62, v126
	s_cmpk_gt_u32 s3, 0x1ff
	v_add_f32_e32 v63, v3, v124
	s_cbranch_scc1 .LBB0_740
	s_lshl_b32 s10, s3, 10
	v_cvt_pk_bf16_f32 v3, v62, v63
	v_lshl_add_u64 v[64:65], v[88:89], 0, s[10:11]
	global_store_short v[64:65], v3, off offset:512
	global_store_short_d16_hi v[64:65], v3, off offset:640
.LBB0_740:
	v_mul_f32_e32 v3, v87, v63
	v_fma_f32 v3, v86, v62, -v3
	v_add_f32_e32 v3, v3, v60
	v_mul_f32_e32 v60, v87, v62
	v_fmac_f32_e32 v60, v86, v63
	s_add_i32 s3, s16, s1
	s_cmpk_gt_u32 s3, 0x1ff
	v_add_f32_e32 v61, v60, v61
	s_cbranch_scc1 .LBB0_742
	s_lshl_b32 s10, s3, 10
	v_cvt_pk_bf16_f32 v60, v3, v61
	v_lshl_add_u64 v[62:63], v[88:89], 0, s[10:11]
	global_store_short v[62:63], v60, off offset:512
	global_store_short_d16_hi v[62:63], v60, off offset:640
.LBB0_742:
	v_mul_f32_e32 v60, v87, v61
	v_fma_f32 v60, v86, v3, -v60
	v_mul_f32_e32 v3, v87, v3
	v_fmac_f32_e32 v3, v86, v61
	s_add_i32 s3, s14, s1
	v_add_f32_e32 v60, v60, v122
	s_cmpk_gt_u32 s3, 0x1ff
	v_add_f32_e32 v61, v3, v120
	s_cbranch_scc1 .LBB0_744
	s_lshl_b32 s10, s3, 10
	v_cvt_pk_bf16_f32 v3, v60, v61
	v_lshl_add_u64 v[62:63], v[88:89], 0, s[10:11]
	global_store_short v[62:63], v3, off offset:512
	global_store_short_d16_hi v[62:63], v3, off offset:640
.LBB0_744:
	v_mul_f32_e32 v3, v87, v61
	v_fma_f32 v3, v86, v60, -v3
	v_add_f32_e32 v3, v3, v58
	v_mul_f32_e32 v58, v87, v60
	v_fmac_f32_e32 v58, v86, v61
	s_add_i32 s3, s12, s1
	s_cmpk_gt_u32 s3, 0x1ff
	v_add_f32_e32 v59, v58, v59
	s_cbranch_scc1 .LBB0_746
	s_lshl_b32 s10, s3, 10
	v_cvt_pk_bf16_f32 v58, v3, v59
	v_lshl_add_u64 v[60:61], v[88:89], 0, s[10:11]
	global_store_short v[60:61], v58, off offset:512
	global_store_short_d16_hi v[60:61], v58, off offset:640
.LBB0_746:
	v_mul_f32_e32 v58, v87, v59
	v_fma_f32 v58, v86, v3, -v58
	v_mul_f32_e32 v3, v87, v3
	v_fmac_f32_e32 v3, v86, v59
	s_add_i32 s3, s60, s1
	v_add_f32_e32 v58, v58, v119
	s_cmpk_gt_u32 s3, 0x1ff
	v_add_f32_e32 v59, v3, v118
	s_cbranch_scc1 .LBB0_748
	s_lshl_b32 s10, s3, 10
	v_cvt_pk_bf16_f32 v3, v58, v59
	v_lshl_add_u64 v[60:61], v[88:89], 0, s[10:11]
	global_store_short v[60:61], v3, off offset:512
	global_store_short_d16_hi v[60:61], v3, off offset:640
.LBB0_748:
	v_mul_f32_e32 v3, v87, v59
	v_fma_f32 v3, v86, v58, -v3
	v_add_f32_e32 v3, v3, v56
	v_mul_f32_e32 v56, v87, v58
	v_fmac_f32_e32 v56, v86, v59
	s_add_i32 s3, s58, s1
	s_cmpk_gt_u32 s3, 0x1ff
	v_add_f32_e32 v57, v56, v57
	s_cbranch_scc1 .LBB0_750
	s_lshl_b32 s10, s3, 10
	v_cvt_pk_bf16_f32 v56, v3, v57
	v_lshl_add_u64 v[58:59], v[88:89], 0, s[10:11]
	global_store_short v[58:59], v56, off offset:512
	global_store_short_d16_hi v[58:59], v56, off offset:640
.LBB0_750:
	v_mul_f32_e32 v56, v87, v57
	v_fma_f32 v56, v86, v3, -v56
	v_mul_f32_e32 v3, v87, v3
	v_fmac_f32_e32 v3, v86, v57
	s_add_i32 s3, s56, s1
	v_add_f32_e32 v56, v56, v117
	s_cmpk_gt_u32 s3, 0x1ff
	v_add_f32_e32 v57, v3, v116
	s_cbranch_scc1 .LBB0_752
	s_lshl_b32 s10, s3, 10
	v_cvt_pk_bf16_f32 v3, v56, v57
	v_lshl_add_u64 v[58:59], v[88:89], 0, s[10:11]
	global_store_short v[58:59], v3, off offset:512
	global_store_short_d16_hi v[58:59], v3, off offset:640
.LBB0_752:
	v_mul_f32_e32 v3, v87, v57
	v_fma_f32 v3, v86, v56, -v3
	v_add_f32_e32 v3, v3, v54
	v_mul_f32_e32 v54, v87, v56
	v_fmac_f32_e32 v54, v86, v57
	s_add_i32 s3, s54, s1
	s_cmpk_gt_u32 s3, 0x1ff
	v_add_f32_e32 v55, v54, v55
	s_cbranch_scc1 .LBB0_754
	s_lshl_b32 s10, s3, 10
	v_cvt_pk_bf16_f32 v54, v3, v55
	v_lshl_add_u64 v[56:57], v[88:89], 0, s[10:11]
	global_store_short v[56:57], v54, off offset:512
	global_store_short_d16_hi v[56:57], v54, off offset:640
.LBB0_754:
	v_mul_f32_e32 v54, v87, v55
	v_fma_f32 v54, v86, v3, -v54
	v_mul_f32_e32 v3, v87, v3
	v_fmac_f32_e32 v3, v86, v55
	s_add_i32 s3, s52, s1
	v_add_f32_e32 v54, v54, v115
	s_cmpk_gt_u32 s3, 0x1ff
	v_add_f32_e32 v55, v3, v114
	s_cbranch_scc1 .LBB0_756
	s_lshl_b32 s10, s3, 10
	v_cvt_pk_bf16_f32 v3, v54, v55
	v_lshl_add_u64 v[56:57], v[88:89], 0, s[10:11]
	global_store_short v[56:57], v3, off offset:512
	global_store_short_d16_hi v[56:57], v3, off offset:640
.LBB0_756:
	v_mul_f32_e32 v3, v87, v55
	v_fma_f32 v3, v86, v54, -v3
	v_add_f32_e32 v3, v3, v52
	v_mul_f32_e32 v52, v87, v54
	v_fmac_f32_e32 v52, v86, v55
	s_add_i32 s3, s76, s1
	s_cmpk_gt_u32 s3, 0x1ff
	v_add_f32_e32 v53, v52, v53
	s_cbranch_scc1 .LBB0_758
	s_lshl_b32 s10, s3, 10
	v_cvt_pk_bf16_f32 v52, v3, v53
	v_lshl_add_u64 v[54:55], v[88:89], 0, s[10:11]
	global_store_short v[54:55], v52, off offset:512
	global_store_short_d16_hi v[54:55], v52, off offset:640
.LBB0_758:
	v_mul_f32_e32 v52, v87, v53
	v_fma_f32 v52, v86, v3, -v52
	v_mul_f32_e32 v3, v87, v3
	v_fmac_f32_e32 v3, v86, v53
	s_add_i32 s3, s44, s1
	v_add_f32_e32 v52, v52, v113
	s_cmpk_gt_u32 s3, 0x1ff
	v_add_f32_e32 v53, v3, v112
	s_cbranch_scc1 .LBB0_760
	s_lshl_b32 s10, s3, 10
	v_cvt_pk_bf16_f32 v3, v52, v53
	v_lshl_add_u64 v[54:55], v[88:89], 0, s[10:11]
	global_store_short v[54:55], v3, off offset:512
	global_store_short_d16_hi v[54:55], v3, off offset:640
.LBB0_760:
	v_mul_f32_e32 v3, v87, v53
	v_fma_f32 v3, v86, v52, -v3
	v_add_f32_e32 v3, v3, v50
	v_mul_f32_e32 v50, v87, v52
	v_fmac_f32_e32 v50, v86, v53
	s_add_i32 s2, s2, s1
	s_cmpk_gt_u32 s2, 0x1ff
	v_add_f32_e32 v51, v50, v51
	s_cbranch_scc1 .LBB0_762
	s_lshl_b32 s10, s2, 10
	v_cvt_pk_bf16_f32 v50, v3, v51
	v_lshl_add_u64 v[52:53], v[88:89], 0, s[10:11]
	global_store_short v[52:53], v50, off offset:512
	global_store_short_d16_hi v[52:53], v50, off offset:640
; __device__ __forceinline__ unsigned f2bf(float f) { unsigned u = __builtin_bit_cast(unsigned, f); return (u + 0x7fffu + ((u >> 16) & 1u)) >> 16; }
; __global__ void __launch_bounds__(NWAVES * 64, 2) mega_fwd(Args args) {
;     ...
;             for (int q = 0; q < 64; ++q) { const int sidx = seg * 64 + q, c = dir ? 511 - sidx : sidx; const float nr = ar * sr - ai * si + er[q], ni = ar * si + ai * sr + ei[q]; sr = nr; si = ni;
;                 const int cd = dir ? c - 1 : c + 1;
;                 if (cd >= 0 && cd < 512) { Ab[(size_t)cd * 512] = (bf16)f2bf(sr); Ab[(size_t)cd * 512 + 64] = (bf16)f2bf(si); } }
.LBB0_762:
	v_mul_f32_e32 v50, v87, v51
	v_fma_f32 v50, v86, v3, -v50
	v_mul_f32_e32 v3, v87, v3
	v_fmac_f32_e32 v3, v86, v51
	s_add_i32 s2, s68, s1
	v_add_f32_e32 v50, v50, v111
	s_cmpk_gt_u32 s2, 0x1ff
	v_add_f32_e32 v51, v3, v110
	s_cbranch_scc1 .LBB0_764
	s_lshl_b32 s10, s2, 10
	v_cvt_pk_bf16_f32 v3, v50, v51
	v_lshl_add_u64 v[52:53], v[88:89], 0, s[10:11]
	global_store_short v[52:53], v3, off offset:512
	global_store_short_d16_hi v[52:53], v3, off offset:640
.LBB0_764:
	v_mul_f32_e32 v3, v87, v51
	v_fma_f32 v3, v86, v50, -v3
	v_add_f32_e32 v3, v3, v48
	v_mul_f32_e32 v48, v87, v50
	v_fmac_f32_e32 v48, v86, v51
	s_add_i32 s0, s0, s1
	s_cmpk_gt_u32 s0, 0x1ff
	v_add_f32_e32 v49, v48, v49
	s_cbranch_scc1 .LBB0_766
	s_lshl_b32 s10, s0, 10
	v_cvt_pk_bf16_f32 v48, v3, v49
	v_lshl_add_u64 v[50:51], v[88:89], 0, s[10:11]
	global_store_short v[50:51], v48, off offset:512
	global_store_short_d16_hi v[50:51], v48, off offset:640
.LBB0_766:
	v_mul_f32_e32 v48, v87, v49
	v_fma_f32 v48, v86, v3, -v48
	v_mul_f32_e32 v3, v87, v3
	v_fmac_f32_e32 v3, v86, v49
	s_add_i32 s0, s46, s1
	v_add_f32_e32 v48, v48, v109
	s_cmpk_gt_u32 s0, 0x1ff
	v_add_f32_e32 v49, v3, v108
	s_cbranch_scc1 .LBB0_768
	s_lshl_b32 s10, s0, 10
	v_cvt_pk_bf16_f32 v3, v48, v49
	v_lshl_add_u64 v[50:51], v[88:89], 0, s[10:11]
	global_store_short v[50:51], v3, off offset:512
	global_store_short_d16_hi v[50:51], v3, off offset:640
.LBB0_768:
	v_mul_f32_e32 v3, v87, v49
	v_fma_f32 v3, v86, v48, -v3
	v_add_f32_e32 v3, v3, v46
	v_mul_f32_e32 v46, v87, v48
	v_fmac_f32_e32 v46, v86, v49
	s_add_i32 s0, s42, s1
	s_cmpk_gt_u32 s0, 0x1ff
	v_add_f32_e32 v47, v46, v47
	s_cbranch_scc1 .LBB0_770
	s_lshl_b32 s10, s0, 10
	v_cvt_pk_bf16_f32 v46, v3, v47
	v_lshl_add_u64 v[48:49], v[88:89], 0, s[10:11]
	global_store_short v[48:49], v46, off offset:512
	global_store_short_d16_hi v[48:49], v46, off offset:640
.LBB0_770:
	v_mul_f32_e32 v46, v87, v47
	v_fma_f32 v46, v86, v3, -v46
	v_mul_f32_e32 v3, v87, v3
	v_fmac_f32_e32 v3, v86, v47
	s_add_i32 s0, s34, s1
	v_add_f32_e32 v46, v46, v107
	s_cmpk_gt_u32 s0, 0x1ff
	v_add_f32_e32 v47, v3, v106
	s_cbranch_scc1 .LBB0_772
	s_lshl_b32 s10, s0, 10
	v_cvt_pk_bf16_f32 v3, v46, v47
	v_lshl_add_u64 v[48:49], v[88:89], 0, s[10:11]
	global_store_short v[48:49], v3, off offset:512
	global_store_short_d16_hi v[48:49], v3, off offset:640
.LBB0_772:
	v_mul_f32_e32 v3, v87, v47
	v_fma_f32 v3, v86, v46, -v3
	v_add_f32_e32 v3, v3, v44
	v_mul_f32_e32 v44, v87, v46
	v_fmac_f32_e32 v44, v86, v47
	s_add_i32 s0, s70, s1
	s_cmpk_gt_u32 s0, 0x1ff
	v_add_f32_e32 v45, v44, v45
	s_cbranch_scc1 .LBB0_774
	s_lshl_b32 s10, s0, 10
	v_cvt_pk_bf16_f32 v44, v3, v45
	v_lshl_add_u64 v[46:47], v[88:89], 0, s[10:11]
	global_store_short v[46:47], v44, off offset:512
	global_store_short_d16_hi v[46:47], v44, off offset:640
.LBB0_774:
	v_mul_f32_e32 v44, v87, v45
	v_fma_f32 v44, v86, v3, -v44
	v_mul_f32_e32 v3, v87, v3
	v_fmac_f32_e32 v3, v86, v45
	s_add_i32 s0, s30, s1
	v_add_f32_e32 v44, v44, v105
	s_cmpk_gt_u32 s0, 0x1ff
	v_add_f32_e32 v45, v3, v104
	s_cbranch_scc1 .LBB0_776
	s_lshl_b32 s10, s0, 10
	v_cvt_pk_bf16_f32 v3, v44, v45
	v_lshl_add_u64 v[46:47], v[88:89], 0, s[10:11]
	global_store_short v[46:47], v3, off offset:512
	global_store_short_d16_hi v[46:47], v3, off offset:640
.LBB0_776:
	v_mul_f32_e32 v3, v87, v45
	v_fma_f32 v3, v86, v44, -v3
	v_add_f32_e32 v3, v3, v42
	v_mul_f32_e32 v42, v87, v44
	v_fmac_f32_e32 v42, v86, v45
	s_add_i32 s0, s28, s1
	s_cmpk_gt_u32 s0, 0x1ff
	v_add_f32_e32 v43, v42, v43
	s_cbranch_scc1 .LBB0_778
	s_lshl_b32 s10, s0, 10
	v_cvt_pk_bf16_f32 v42, v3, v43
	v_lshl_add_u64 v[44:45], v[88:89], 0, s[10:11]
	global_store_short v[44:45], v42, off offset:512
	global_store_short_d16_hi v[44:45], v42, off offset:640
.LBB0_778:
	v_mul_f32_e32 v42, v87, v43
	v_fma_f32 v42, v86, v3, -v42
	v_mul_f32_e32 v3, v87, v3
	v_readlane_b32 s2, v254, 50
	v_fmac_f32_e32 v3, v86, v43
	s_add_i32 s0, s2, s1
	v_add_f32_e32 v42, v42, v103
	s_cmpk_gt_u32 s0, 0x1ff
	v_add_f32_e32 v43, v3, v102
	v_readlane_b32 s3, v254, 51
	s_cbranch_scc1 .LBB0_780
	s_lshl_b32 s10, s0, 10
	v_cvt_pk_bf16_f32 v3, v42, v43
	v_lshl_add_u64 v[44:45], v[88:89], 0, s[10:11]
	global_store_short v[44:45], v3, off offset:512
	global_store_short_d16_hi v[44:45], v3, off offset:640
.LBB0_780:
	v_mul_f32_e32 v3, v87, v43
	v_fma_f32 v3, v86, v42, -v3
	v_add_f32_e32 v3, v3, v40
	v_mul_f32_e32 v40, v87, v42
	v_readlane_b32 s2, v254, 52
	v_fmac_f32_e32 v40, v86, v43
	s_add_i32 s0, s2, s1
	s_cmpk_gt_u32 s0, 0x1ff
	v_add_f32_e32 v41, v40, v41
	s_mov_b32 s88, s67
	v_readlane_b32 s3, v254, 53
	s_cbranch_scc1 .LBB0_782
	s_lshl_b32 s10, s0, 10
	v_cvt_pk_bf16_f32 v40, v3, v41
	v_lshl_add_u64 v[42:43], v[88:89], 0, s[10:11]
	global_store_short v[42:43], v40, off offset:512
	global_store_short_d16_hi v[42:43], v40, off offset:640
.LBB0_782:
	v_mul_f32_e32 v40, v87, v41
	v_fma_f32 v40, v86, v3, -v40
	v_mul_f32_e32 v3, v87, v3
	v_readlane_b32 s2, v254, 54
	v_fmac_f32_e32 v3, v86, v41
	s_add_i32 s0, s2, s1
	v_add_f32_e32 v40, v40, v101
	s_cmpk_gt_u32 s0, 0x1ff
	v_add_f32_e32 v41, v3, v100
	v_readlane_b32 s3, v254, 55
	s_cbranch_scc1 .LBB0_784
	s_lshl_b32 s10, s0, 10
	v_cvt_pk_bf16_f32 v3, v40, v41
	v_lshl_add_u64 v[42:43], v[88:89], 0, s[10:11]
	global_store_short v[42:43], v3, off offset:512
	global_store_short_d16_hi v[42:43], v3, off offset:640
.LBB0_784:
	v_mul_f32_e32 v3, v87, v41
	v_fma_f32 v3, v86, v40, -v3
	v_add_f32_e32 v3, v3, v38
	v_mul_f32_e32 v38, v87, v40
	v_readlane_b32 s2, v254, 56
	v_fmac_f32_e32 v38, v86, v41
	s_add_i32 s0, s2, s1
	s_cmpk_gt_u32 s0, 0x1ff
	v_add_f32_e32 v39, v38, v39
	v_readlane_b32 s3, v254, 57
	s_cbranch_scc1 .LBB0_786
	s_lshl_b32 s10, s0, 10
	v_cvt_pk_bf16_f32 v38, v3, v39
	v_lshl_add_u64 v[40:41], v[88:89], 0, s[10:11]
	global_store_short v[40:41], v38, off offset:512
	global_store_short_d16_hi v[40:41], v38, off offset:640
; __device__ __forceinline__ unsigned f2bf(float f) { unsigned u = __builtin_bit_cast(unsigned, f); return (u + 0x7fffu + ((u >> 16) & 1u)) >> 16; }
; __global__ void __launch_bounds__(NWAVES * 64, 2) mega_fwd(Args args) {
;     ...
;             for (int q = 0; q < 64; ++q) { const int sidx = seg * 64 + q, c = dir ? 511 - sidx : sidx; const float nr = ar * sr - ai * si + er[q], ni = ar * si + ai * sr + ei[q]; sr = nr; si = ni;
;                 const int cd = dir ? c - 1 : c + 1;
;                 if (cd >= 0 && cd < 512) { Ab[(size_t)cd * 512] = (bf16)f2bf(sr); Ab[(size_t)cd * 512 + 64] = (bf16)f2bf(si); } }
.LBB0_786:
	v_mul_f32_e32 v38, v87, v39
	v_fma_f32 v38, v86, v3, -v38
	v_mul_f32_e32 v3, v87, v3
	v_readlane_b32 s2, v254, 58
	v_fmac_f32_e32 v3, v86, v39
	s_add_i32 s0, s2, s1
	v_add_f32_e32 v38, v38, v99
	s_cmpk_gt_u32 s0, 0x1ff
	v_add_f32_e32 v39, v3, v98
	v_readlane_b32 s3, v254, 59
	s_cbranch_scc1 .LBB0_788
	s_lshl_b32 s10, s0, 10
	v_cvt_pk_bf16_f32 v3, v38, v39
	v_lshl_add_u64 v[40:41], v[88:89], 0, s[10:11]
	global_store_short v[40:41], v3, off offset:512
	global_store_short_d16_hi v[40:41], v3, off offset:640
.LBB0_788:
	v_mul_f32_e32 v3, v87, v39
	v_fma_f32 v3, v86, v38, -v3
	v_add_f32_e32 v3, v3, v37
	v_mul_f32_e32 v37, v87, v38
	v_readlane_b32 s2, v254, 60
	v_fmac_f32_e32 v37, v86, v39
	s_add_i32 s0, s2, s1
	s_cmpk_gt_u32 s0, 0x1ff
	v_add_f32_e32 v36, v37, v36
	v_readlane_b32 s3, v254, 61
	s_cbranch_scc1 .LBB0_790
	s_lshl_b32 s10, s0, 10
	v_cvt_pk_bf16_f32 v37, v3, v36
	v_lshl_add_u64 v[38:39], v[88:89], 0, s[10:11]
	global_store_short v[38:39], v37, off offset:512
	global_store_short_d16_hi v[38:39], v37, off offset:640
.LBB0_790:
	v_mul_f32_e32 v37, v87, v36
	v_fma_f32 v37, v86, v3, -v37
	v_mul_f32_e32 v3, v87, v3
	v_readlane_b32 s2, v254, 62
	v_fmac_f32_e32 v3, v86, v36
	s_add_i32 s0, s2, s1
	v_add_f32_e32 v35, v37, v35
	s_cmpk_gt_u32 s0, 0x1ff
	v_add_f32_e32 v34, v3, v34
	v_readlane_b32 s3, v254, 63
	s_cbranch_scc1 .LBB0_792
	s_lshl_b32 s10, s0, 10
	v_cvt_pk_bf16_f32 v3, v35, v34
	v_lshl_add_u64 v[36:37], v[88:89], 0, s[10:11]
	global_store_short v[36:37], v3, off offset:512
	global_store_short_d16_hi v[36:37], v3, off offset:640
.LBB0_792:
	v_mul_f32_e32 v3, v87, v34
	v_fma_f32 v3, v86, v35, -v3
	v_add_f32_e32 v3, v3, v33
	v_mul_f32_e32 v33, v87, v35
	v_readlane_b32 s2, v250, 0
	v_fmac_f32_e32 v33, v86, v34
	s_add_i32 s0, s2, s1
	s_cmpk_gt_u32 s0, 0x1ff
	v_add_f32_e32 v32, v33, v32
	v_readlane_b32 s3, v250, 1
	s_cbranch_scc1 .LBB0_794
	s_lshl_b32 s10, s0, 10
	v_cvt_pk_bf16_f32 v33, v3, v32
	v_lshl_add_u64 v[34:35], v[88:89], 0, s[10:11]
	global_store_short v[34:35], v33, off offset:512
	global_store_short_d16_hi v[34:35], v33, off offset:640
.LBB0_794:
	v_mul_f32_e32 v33, v87, v32
	v_fma_f32 v33, v86, v3, -v33
	v_mul_f32_e32 v3, v87, v3
	v_readlane_b32 s2, v250, 2
	v_fmac_f32_e32 v3, v86, v32
	s_add_i32 s0, s2, s1
	v_add_f32_e32 v31, v33, v31
	s_cmpk_gt_u32 s0, 0x1ff
	v_add_f32_e32 v30, v3, v30
	v_readlane_b32 s3, v250, 3
	s_cbranch_scc1 .LBB0_796
	s_lshl_b32 s10, s0, 10
	v_cvt_pk_bf16_f32 v3, v31, v30
	v_lshl_add_u64 v[32:33], v[88:89], 0, s[10:11]
	global_store_short v[32:33], v3, off offset:512
	global_store_short_d16_hi v[32:33], v3, off offset:640
.LBB0_796:
	v_mul_f32_e32 v3, v87, v30
	v_fma_f32 v3, v86, v31, -v3
	v_add_f32_e32 v3, v3, v28
	v_mul_f32_e32 v28, v87, v31
	v_readlane_b32 s2, v250, 4
	v_fmac_f32_e32 v28, v86, v30
	s_add_i32 s0, s2, s1
	s_cmpk_gt_u32 s0, 0x1ff
	v_add_f32_e32 v28, v28, v29
	v_readlane_b32 s3, v250, 5
	s_cbranch_scc1 .LBB0_798
	s_lshl_b32 s10, s0, 10
	v_cvt_pk_bf16_f32 v29, v3, v28
	v_lshl_add_u64 v[30:31], v[88:89], 0, s[10:11]
	global_store_short v[30:31], v29, off offset:512
	global_store_short_d16_hi v[30:31], v29, off offset:640
.LBB0_798:
	v_mul_f32_e32 v29, v87, v28
	v_fma_f32 v29, v86, v3, -v29
	v_mul_f32_e32 v3, v87, v3
	v_readlane_b32 s2, v250, 6
	v_fmac_f32_e32 v3, v86, v28
	s_add_i32 s0, s2, s1
	v_add_f32_e32 v26, v29, v26
	s_cmpk_gt_u32 s0, 0x1ff
	v_add_f32_e32 v27, v3, v27
	v_readlane_b32 s3, v250, 7
	s_cbranch_scc1 .LBB0_800
	s_lshl_b32 s10, s0, 10
	v_cvt_pk_bf16_f32 v3, v26, v27
	v_lshl_add_u64 v[28:29], v[88:89], 0, s[10:11]
	global_store_short v[28:29], v3, off offset:512
	global_store_short_d16_hi v[28:29], v3, off offset:640
.LBB0_800:
	v_mul_f32_e32 v3, v87, v27
	v_fma_f32 v3, v86, v26, -v3
	v_add_f32_e32 v3, v3, v24
	v_mul_f32_e32 v24, v87, v26
	v_readlane_b32 s2, v250, 8
	v_fmac_f32_e32 v24, v86, v27
	s_add_i32 s0, s2, s1
	s_cmpk_gt_u32 s0, 0x1ff
	v_add_f32_e32 v24, v24, v25
	v_readlane_b32 s3, v250, 9
	s_cbranch_scc1 .LBB0_802
	s_lshl_b32 s10, s0, 10
	v_cvt_pk_bf16_f32 v25, v3, v24
	v_lshl_add_u64 v[26:27], v[88:89], 0, s[10:11]
	global_store_short v[26:27], v25, off offset:512
	global_store_short_d16_hi v[26:27], v25, off offset:640
; __device__ __forceinline__ unsigned f2bf(float f) { unsigned u = __builtin_bit_cast(unsigned, f); return (u + 0x7fffu + ((u >> 16) & 1u)) >> 16; }
; __global__ void __launch_bounds__(NWAVES * 64, 2) mega_fwd(Args args) {
;     ...
;             for (int q = 0; q < 64; ++q) { const int sidx = seg * 64 + q, c = dir ? 511 - sidx : sidx; const float nr = ar * sr - ai * si + er[q], ni = ar * si + ai * sr + ei[q]; sr = nr; si = ni;
;                 const int cd = dir ? c - 1 : c + 1;
;                 if (cd >= 0 && cd < 512) { Ab[(size_t)cd * 512] = (bf16)f2bf(sr); Ab[(size_t)cd * 512 + 64] = (bf16)f2bf(si); } }
.LBB0_802:
	v_mul_f32_e32 v25, v87, v24
	v_fma_f32 v25, v86, v3, -v25
	v_mul_f32_e32 v3, v87, v3
	v_readlane_b32 s2, v250, 10
	v_fmac_f32_e32 v3, v86, v24
	s_add_i32 s0, s2, s1
	v_add_f32_e32 v22, v25, v22
	s_cmpk_gt_u32 s0, 0x1ff
	v_add_f32_e32 v23, v3, v23
	v_readlane_b32 s3, v250, 11
	s_cbranch_scc1 .LBB0_804
	s_lshl_b32 s10, s0, 10
	v_cvt_pk_bf16_f32 v3, v22, v23
	v_lshl_add_u64 v[24:25], v[88:89], 0, s[10:11]
	global_store_short v[24:25], v3, off offset:512
	global_store_short_d16_hi v[24:25], v3, off offset:640
.LBB0_804:
	v_mul_f32_e32 v3, v87, v23
	v_fma_f32 v3, v86, v22, -v3
	v_add_f32_e32 v3, v3, v20
	v_mul_f32_e32 v20, v87, v22
	v_readlane_b32 s2, v250, 12
	v_fmac_f32_e32 v20, v86, v23
	s_add_i32 s0, s2, s1
	s_cmpk_gt_u32 s0, 0x1ff
	v_add_f32_e32 v20, v20, v21
	v_readlane_b32 s3, v250, 13
	s_cbranch_scc1 .LBB0_806
	s_lshl_b32 s10, s0, 10
	v_cvt_pk_bf16_f32 v21, v3, v20
	v_lshl_add_u64 v[22:23], v[88:89], 0, s[10:11]
	global_store_short v[22:23], v21, off offset:512
	global_store_short_d16_hi v[22:23], v21, off offset:640
.LBB0_806:
	v_mul_f32_e32 v21, v87, v20
	v_fma_f32 v21, v86, v3, -v21
	v_mul_f32_e32 v3, v87, v3
	v_readlane_b32 s2, v250, 14
	v_fmac_f32_e32 v3, v86, v20
	s_add_i32 s0, s2, s1
	v_add_f32_e32 v18, v21, v18
	s_cmpk_gt_u32 s0, 0x1ff
	v_add_f32_e32 v19, v3, v19
	v_readlane_b32 s3, v250, 15
	s_cbranch_scc1 .LBB0_808
	s_lshl_b32 s10, s0, 10
	v_cvt_pk_bf16_f32 v3, v18, v19
	v_lshl_add_u64 v[20:21], v[88:89], 0, s[10:11]
	global_store_short v[20:21], v3, off offset:512
	global_store_short_d16_hi v[20:21], v3, off offset:640
.LBB0_808:
	v_mul_f32_e32 v3, v87, v19
	v_fma_f32 v3, v86, v18, -v3
	v_add_f32_e32 v3, v3, v16
	v_mul_f32_e32 v16, v87, v18
	v_readlane_b32 s2, v250, 16
	v_fmac_f32_e32 v16, v86, v19
	s_add_i32 s0, s2, s1
	s_cmpk_gt_u32 s0, 0x1ff
	v_add_f32_e32 v16, v16, v17
	v_readlane_b32 s3, v250, 17
	s_cbranch_scc1 .LBB0_810
	s_lshl_b32 s10, s0, 10
	v_cvt_pk_bf16_f32 v17, v3, v16
	v_lshl_add_u64 v[18:19], v[88:89], 0, s[10:11]
	global_store_short v[18:19], v17, off offset:512
	global_store_short_d16_hi v[18:19], v17, off offset:640
.LBB0_810:
	v_mul_f32_e32 v17, v87, v16
	v_fma_f32 v17, v86, v3, -v17
	v_mul_f32_e32 v3, v87, v3
	v_readlane_b32 s2, v250, 18
	v_fmac_f32_e32 v3, v86, v16
	s_add_i32 s0, s2, s1
	v_add_f32_e32 v14, v17, v14
	s_cmpk_gt_u32 s0, 0x1ff
	v_add_f32_e32 v3, v3, v15
	v_readlane_b32 s3, v250, 19
	s_cbranch_scc1 .LBB0_812
	s_lshl_b32 s10, s0, 10
	v_cvt_pk_bf16_f32 v15, v14, v3
	v_lshl_add_u64 v[16:17], v[88:89], 0, s[10:11]
	global_store_short v[16:17], v15, off offset:512
	global_store_short_d16_hi v[16:17], v15, off offset:640
.LBB0_812:
	v_mul_f32_e32 v15, v87, v3
	v_fma_f32 v15, v86, v14, -v15
	v_mul_f32_e32 v14, v87, v14
	v_readlane_b32 s2, v250, 20
	v_fmac_f32_e32 v14, v86, v3
	s_add_i32 s0, s2, s1
	v_add_f32_e32 v12, v15, v12
	s_cmpk_gt_u32 s0, 0x1ff
	v_add_f32_e32 v13, v14, v13
	v_readlane_b32 s3, v250, 21
	s_cbranch_scc1 .LBB0_814
	s_lshl_b32 s10, s0, 10
	v_cvt_pk_bf16_f32 v3, v12, v13
	v_lshl_add_u64 v[14:15], v[88:89], 0, s[10:11]
	global_store_short v[14:15], v3, off offset:512
	global_store_short_d16_hi v[14:15], v3, off offset:640
.LBB0_814:
	v_mul_f32_e32 v3, v87, v13
	v_fma_f32 v3, v86, v12, -v3
	v_add_f32_e32 v3, v3, v10
	v_mul_f32_e32 v10, v87, v12
	v_readlane_b32 s2, v252, 0
	v_fmac_f32_e32 v10, v86, v13
	s_add_i32 s0, s2, s1
	s_cmpk_gt_u32 s0, 0x1ff
	v_add_f32_e32 v10, v10, v11
	v_readlane_b32 s3, v252, 1
	s_cbranch_scc1 .LBB0_816
	s_lshl_b32 s10, s0, 10
	v_cvt_pk_bf16_f32 v11, v3, v10
	v_lshl_add_u64 v[12:13], v[88:89], 0, s[10:11]
	global_store_short v[12:13], v11, off offset:512
	global_store_short_d16_hi v[12:13], v11, off offset:640
.LBB0_816:
	v_readlane_b32 s2, v252, 2
	s_add_i32 s0, s2, s1
	s_cmpk_gt_u32 s0, 0x1ff
	v_readlane_b32 s3, v252, 3
	s_cbranch_scc1 .LBB0_678
	v_mul_f32_e32 v11, v87, v3
	v_fmac_f32_e32 v11, v86, v10
	v_add_f32_e32 v11, v11, v9
	v_mul_f32_e32 v9, v87, v10
	v_fma_f32 v3, v86, v3, -v9
	v_add_f32_e32 v3, v3, v8
	s_lshl_b32 s10, s0, 10
	v_cvt_pk_bf16_f32 v3, v3, v11
	v_lshl_add_u64 v[8:9], v[88:89], 0, s[10:11]
	global_store_short v[8:9], v3, off offset:512
	global_store_short_d16_hi v[8:9], v3, off offset:640
	s_branch .LBB0_678

; __device__ __forceinline__ unsigned xb_ld(unsigned* p)              { return __hip_atomic_load(p, __ATOMIC_RELAXED, __HIP_MEMORY_SCOPE_AGENT); }
; __device__ __forceinline__ unsigned xb_add(unsigned* p, unsigned v) { return __hip_atomic_fetch_add(p, v, __ATOMIC_RELAXED, __HIP_MEMORY_SCOPE_AGENT); }
; #define XB_SPIN(cond, bar) do { unsigned _sp = 0; while (cond) { __builtin_amdgcn_s_sleep(1); \
;     if ((++_sp & 255u) == 0u) { if (xb_ld(&(bar)[XB_TMO])) break; if (_sp > XB_SPIN_CAP) { atomicAdd(&(bar)[XB_TMO], 1u); break; } } } } while (0)
; __device__ __forceinline__ void xcd_barrier(const XcdBarrier& b) {
;     asm volatile("s_waitcnt vmcnt(0)" ::: "memory");
;     __syncthreads();
;     if (threadIdx.x == 0) {
;         unsigned* bar = b.bar;
;         __builtin_amdgcn_s_waitcnt(0);
;         unsigned nloc = b.st[0], nx = b.st[1];
;         if (nloc == 0u) { xcd_barrier_complete(bar, b.x, nloc, nx); b.st[0] = nloc; b.st[1] = nx; }
;         const unsigned old = xb_add(&bar[XB_XSUB(b.x)], 1u);
;         const unsigned gen = old / nloc;
;         if (old + 1u == (gen + 1u) * nloc) {
;             __builtin_amdgcn_fence(__ATOMIC_RELEASE, "agent");
;             asm volatile("s_waitcnt vmcnt(0)" ::: "memory");
;             const unsigned og = xb_add(&bar[XB_TOP], 1u);
;             const unsigned tg = og / nx;
;             if (og + 1u == (tg + 1u) * nx) xb_add(&bar[XB_TOPGEN], 1u);
;             else XB_SPIN(xb_ld(&bar[XB_TOPGEN]) == tg, bar);
;             __builtin_amdgcn_fence(__ATOMIC_ACQUIRE, "agent");
;             xb_add(&bar[XB_XGEN(b.x)], 1u);
;             asm volatile("s_waitcnt vmcnt(0)" ::: "memory");
;         } else {
;             XB_SPIN(xb_ld(&bar[XB_XGEN(b.x)]) == gen, bar);
;             __builtin_amdgcn_fence(__ATOMIC_ACQUIRE, "agent");
;             asm volatile("s_waitcnt vmcnt(0)" ::: "memory");
;         }
;     }
;     __syncthreads();
; }
.LBB0_1235:
	s_cmp_gt_i32 s85, 10
	s_cselect_b64 s[2:3], -1, 0
	s_and_b64 s[0:1], s[0:1], s[2:3]
	s_andn2_b64 vcc, exec, s[0:1]
	s_cbranch_vccnz .LBB0_1289
	s_waitcnt vmcnt(0)
	s_waitcnt vmcnt(0) lgkmcnt(0)
	s_barrier
	s_and_saveexec_b64 s[0:1], s[74:75]
	s_cbranch_execz .LBB0_1288
	buffer_inv sc1
	s_and_b32 s4, s88, 7
	s_lshl_b32 s4, s4, 3
	s_bfe_u32 s5, s88, 0x30003
	s_or_b32 s4, s4, s5
	s_lshl_b32 s4, s4, 8
	s_add_u32 s6, s66, 0xfd09000
	s_addc_u32 s7, s67, 0
	v_mov_b32_e32 v1, s4
	v_mov_b32_e32 v2, 1
	global_atomic_add v1, v2, s[6:7]
	s_movk_i32 s5, 16
	s_mov_b32 s8, 0
	v_mov_b32_e32 v5, 0x5000
